# placement: F3 loop head at 8 mod 64 (F1G 56, FFN-F2 40)
# baseline (speedup 1.0000x reference)
.LBB0_1154:
	s_lshl_b32 s6, s20, 1
	s_or_b32 s13, s6, 1
	s_mul_i32 s7, s13, 0x3000
	s_mul_hi_u32 s6, s13, 0x3000
	s_add_u32 s7, s18, s7
	s_addc_u32 s6, s19, s6
	s_add_u32 s42, s7, 0x20000
	s_addc_u32 s43, s6, 0
	s_lshl_b32 s72, s20, 11
	s_lshl_b64 s[6:7], s[72:73], 2
	s_waitcnt lgkmcnt(0)
	s_add_u32 s36, s4, s6
	s_addc_u32 s37, s5, s7
	s_add_u32 s14, s18, 0x40000
	s_mul_i32 s4, s20, 0xc000
	s_addc_u32 s15, s19, 0
	s_add_i32 s6, s4, 0xc000
	s_and_b64 s[4:5], exec, s[8:9]
	s_cselect_b32 s72, 0, s6
	s_lshl_b64 s[4:5], s[72:73], 2
	s_add_u32 s6, s14, s4
	s_addc_u32 s7, s15, s5
	s_mul_hi_u32 s4, s13, 0x18000
	s_mul_i32 s13, s13, 0x18000
	s_add_u32 s40, s14, s13
	s_addc_u32 s41, s15, s4
	s_add_u32 s46, s18, 0x100000
	s_addc_u32 s47, s19, 0
	s_add_u32 s48, s18, 0x10200
	s_addc_u32 s49, s19, 0
	s_and_b32 s8, s3, 3
	s_lshl_b32 s3, s12, 6
	s_lshl_b32 s9, s12, 13
	s_lshl_b32 s13, s8, 12
	s_add_u32 s18, s18, 0x8800000
	s_addc_u32 s19, s19, 0
	s_add_i32 m0, s28, 0x18000
	v_lshl_add_u64 v[6:7], v[6:7], 0, s[74:75]
	s_waitcnt vmcnt(2)
	s_barrier
	global_load_lds_dwordx4 v[6:7], off
	v_lshl_add_u64 v[4:5], v[4:5], 0, s[74:75]
	s_add_i32 m0, s28, 0x1a000
	s_add_i32 s44, s28, 0x8000
	s_add_i32 s45, s28, 0xa000
	global_load_lds_dwordx4 v[4:5], off
	v_lshl_add_u64 v[0:1], v[0:1], 0, s[74:75]
	s_mov_b32 m0, s44
	s_add_u32 s4, s30, 0x160080
	global_load_lds_dwordx4 v[0:1], off
	v_lshl_add_u64 v[0:1], v[2:3], 0, s[74:75]
	s_mov_b32 m0, s45
	s_addc_u32 s5, s31, 0
	global_load_lds_dwordx4 v[0:1], off
	s_add_i32 m0, s28, 0x1c000
	v_lshl_add_u64 v[0:1], s[4:5], 0, v[176:177]
	global_load_lds_dwordx4 v[0:1], off
	v_lshl_add_u64 v[0:1], s[4:5], 0, v[182:183]
	s_add_i32 m0, s28, 0x1e000
	v_lshlrev_b32_e32 v5, 2, v15
	global_load_lds_dwordx4 v[0:1], off
	v_and_b32_e32 v0, 15, v15
	v_bfe_u32 v1, v15, 4, 2
	v_or_b32_e32 v184, s3, v0
	v_lshlrev_b32_e32 v2, 4, v1
	v_lshlrev_b32_e32 v3, 2, v184
	s_cmpk_lt_u32 s2, 0x100
	v_lshl_or_b32 v2, v0, 6, v2
	v_and_b32_e32 v4, 32, v3
	v_and_b32_e32 v5, 32, v5
	s_cselect_b64 s[52:53], -1, 0
	s_add_i32 s2, s3, 0x80
	v_bitop3_b32 v4, v2, s9, v4 bitop3:0xde
	v_bitop3_b32 v204, v2, s13, v5 bitop3:0xde
	v_lshlrev_b32_e32 v2, 4, v0
	v_ashrrev_i32_e32 v185, 31, v184
	v_or_b32_e32 v0, s2, v0
	s_ashr_i32 s2, s3, 31
	v_lshl_add_u64 v[186:187], v[184:185], 2, s[6:7]
	v_mov_b32_e32 v185, s2
	v_lshl_add_u64 v[188:189], v[184:185], 2, s[6:7]
	s_mov_b64 s[2:3], 0xc0
	v_lshl_add_u64 v[194:195], v[188:189], 0, s[2:3]
	s_lshl_b32 s2, s8, 2
	s_lshl_b32 s9, s12, 10
	s_add_i32 s2, s2, 0
	s_add_i32 s2, s2, s9
	s_add_i32 s6, s2, 0x20c00
	v_readlane_b32 s2, v254, 57
	s_movk_i32 s7, 0x1600
	v_lshlrev_b32_e32 v6, 3, v1
	v_cmp_eq_u32_e64 s[4:5], 0, v1
	v_lshl_add_u32 v209, v0, 2, s2
	v_lshrrev_b32_e32 v1, 1, v8
	v_mul_lo_u32 v0, v9, s7
	v_add_u32_e32 v185, s2, v3
	v_mad_u64_u32 v[0:1], s[2:3], v1, s97, v[0:1]
	v_or_b32_e32 v0, v0, v10
	v_lshl_or_b32 v205, s8, 5, v6
	v_add_lshl_u32 v0, v0, v11, 1
	v_mov_b32_e32 v1, v177
	s_mov_b64 s[8:9], 0x160080
	v_lshl_add_u64 v[196:197], v[0:1], 0, s[8:9]
	v_lshrrev_b32_e32 v1, 1, v12
	v_mul_lo_u32 v0, v13, s7
	v_mad_u64_u32 v[0:1], s[2:3], v1, s97, v[0:1]
	s_waitcnt vmcnt(6)
	s_cmp_eq_u64 s[16:17], 0
	v_or_b32_e32 v0, v0, v14
	s_cselect_b64 s[54:55], -1, 0
	s_cmp_lg_u64 s[16:17], 0
	v_add_lshl_u32 v0, v0, v16, 1
	v_mov_b32_e32 v1, v177
	s_mov_b32 s58, 0
	v_lshl_add_u64 v[190:191], v[188:189], 0, 64
	v_lshl_add_u64 v[192:193], v[188:189], 0, s[74:75]
	s_cselect_b64 s[56:57], -1, 0
	v_add_u32_e32 v206, 64, v185
	v_add_u32_e32 v207, 0x80, v185
	v_add_u32_e32 v208, 0xc0, v185
	v_add_u32_e32 v220, 64, v209
	v_add_u32_e32 v221, 0x80, v209
	v_add_u32_e32 v222, 0xc0, v209
	v_lshl_add_u64 v[198:199], v[0:1], 0, s[8:9]
	v_add_u32_e32 v223, 0, v4
	v_add_u32_e32 v224, s6, v2
	s_mov_b32 s60, s94
	s_mov_b32 s62, s90
	s_mov_b64 s[68:69], s[0:1]
	s_barrier
	s_branch .LBB0_1157
	s_nop 0
	s_nop 0
	s_nop 0
	s_nop 0
